# attention: V^T LDS tile re-laid (144 B rows, permuted key order) so PV fragments are single ds_read_b128
# baseline (speedup 1.0000x reference)
; #define LAS __attribute__((address_space(3)))
; DI int opaque_tid() { int t = threadIdx.x; asm volatile("" : "+v"(t)); return t; }
; __device__ __forceinline__ void attn_phase(LAS unsigned char* ldsb, bf16_t* P, const bf16_t* Kn, const bf16_t* KPE, const bf16_t* VT) {
;     LAS bf16_t* sK = (LAS bf16_t*)(ldsb + A_K); LAS bf16_t* sVt = (LAS bf16_t*)(ldsb + A_VT);
;     const int tid0 = opaque_tid();
;     const int G = gridDim.x, bx = blockIdx.x, vcu = (G % 8 == 0) ? (bx % 8) * (G / 8) + bx / 8 : bx;
;     for (int item = vcu; item < 512; item += G) {
;         const int bh = item >> 3, jq = item & 7, b = bh >> 3, h = bh & 7;
;         const size_t rowbase = (size_t)b * SEQ_T;
;         const bf16_t* vtb = VT + (size_t)(b * 8 + h) * 128 * SEQ_T;
.LBB0_1508:
	s_add_u32 s14, s26, 0x41a0000
	s_movk_i32 s18, 0xff00
	s_addc_u32 s15, s27, 0
	s_mov_b32 s17, 0
	s_movk_i32 s5, 0x2600
	v_mov_b64_e32 v[224:225], s[40:41]
	v_mov_b32_e32 v1, 0
	s_mov_b32 s20, 0x2aaaaaab
	s_mov_b32 s19, -1
	s_movk_i32 s21, 0x190
	s_movk_i32 s29, 0x6400
	s_movk_i32 s30, 0x90
	s_mov_b64 s[52:53], 0x80
	s_mov_b64 s[54:55], 0x2000
	s_mov_b64 s[56:57], 0x20000
	s_mov_b64 s[58:59], 0x1800
	s_movk_i32 s31, 0x1000
	v_mov_b32_e32 v233, 0xff800000
	v_mbcnt_hi_u32_b32 v234, -1, v231
	s_branch .LBB0_1510

; __device__ __forceinline__ void attn_phase(LAS unsigned char* ldsb, bf16_t* P, const bf16_t* Kn, const bf16_t* KPE, const bf16_t* VT) {
;     ...
;             const int lane = tid & 63, w = __builtin_amdgcn_readfirstlane(tid >> 6), r = lane & 31, hh = lane >> 5;
;             const int qb = half ? 15 - jq : jq, q0 = qb * 256, nt = (q0 + 256) >> 6;
;             const int qabs = q0 + w * 32 + r;
;             bf16x8 qf[12];
;             { const bf16_t* qp = P + (rowbase + qabs) * LDP;
; #pragma unroll
;               for (int ks = 0; ks < 8; ++ks) qf[ks] = *(const bf16x8*)(qp + h * 128 + ks * 16 + hh * 8);
; #pragma unroll
;               for (int ks = 0; ks < 4; ++ks) qf[8 + ks] = *(const bf16x8*)(qp + 1024 + h * 64 + ks * 16 + hh * 8); }
;             f32x16 o[4];
; #pragma unroll
;             for (int d = 0; d < 4; ++d) for (int i = 0; i < 16; ++i) o[d][i] = 0.f;
;             float mrun = -INFINITY, lrun = 0.f;
;             u32x4 kst[3], vst[2];
;     ...
;                         const unsigned va0 = (unsigned)(size_t)(sVt + r * 68 + 4 * hh), va1 = va0 + 32 * 68 * 2, va2 = va0 + 64 * 68 * 2, va3 = va0 + 96 * 68 * 2;
.LBB0_1512:
	v_mov_b32_e32 v22, v232
	s_and_b64 s[6:7], s[76:77], exec
	v_readfirstlane_b32 s8, v22
	s_cselect_b32 s12, s33, s44
	s_ashr_i32 s6, s8, 1
	s_and_b32 s45, s6, 0xffffffe0
	v_and_b32_e32 v6, 31, v22
	s_add_i32 s45, s45, s12
	v_or_b32_e32 v228, s45, v6
	v_ashrrev_i32_e32 v229, 31, v228
	v_lshl_add_u64 v[2:3], s[60:61], 0, v[228:229]
	v_mad_u64_u32 v[226:227], s[6:7], v2, s5, v[224:225]
	v_bfe_u32 v12, v22, 5, 1
	v_mad_i32_i24 v227, v3, s5, v227
	v_lshl_add_u64 v[2:3], v[226:227], 0, s[16:17]
	v_lshlrev_b32_e32 v0, 4, v12
	v_lshl_add_u64 v[2:3], v[2:3], 0, v[0:1]
	global_load_dwordx4 v[220:223], v[2:3], off
	global_load_dwordx4 v[216:219], v[2:3], off offset:32
	global_load_dwordx4 v[212:215], v[2:3], off offset:64
	global_load_dwordx4 v[208:211], v[2:3], off offset:96
	global_load_dwordx4 v[204:207], v[2:3], off offset:128
	global_load_dwordx4 v[200:203], v[2:3], off offset:160
	global_load_dwordx4 v[196:199], v[2:3], off offset:192
	global_load_dwordx4 v[192:195], v[2:3], off offset:224
	v_lshl_add_u64 v[2:3], v[226:227], 0, s[72:73]
	v_lshl_add_u64 v[2:3], v[2:3], 0, v[0:1]
	global_load_dwordx4 v[188:191], v[2:3], off offset:2048
	global_load_dwordx4 v[184:187], v[2:3], off offset:2080
	global_load_dwordx4 v[180:183], v[2:3], off offset:2112
	global_load_dwordx4 v[176:179], v[2:3], off offset:2144
	v_mul_hi_i32 v0, v22, s20
	v_lshrrev_b32_e32 v2, 31, v0
	v_ashrrev_i32_e32 v0, 2, v0
	v_add_u32_e32 v2, v0, v2
	v_mul_lo_u32 v0, v2, 24
	v_sub_u32_e32 v23, v22, v0
	v_ashrrev_i32_e32 v3, 31, v2
	v_cmp_gt_i32_e64 s[6:7], 16, v23
	v_cmp_lt_i32_e32 vcc, 15, v23
	v_lshl_add_u64 v[10:11], s[60:61], 0, v[2:3]
	v_lshlrev_b32_e32 v4, 3, v23
	s_and_saveexec_b64 s[8:9], vcc
	s_xor_b64 s[8:9], exec, s[8:9]
	v_lshlrev_b64 v[8:9], 7, v[10:11]
	v_lshl_add_u64 v[8:9], s[14:15], 0, v[8:9]
	v_mov_b32_e32 v5, v1
	v_lshl_add_u64 v[8:9], v[4:5], 1, v[8:9]
	v_lshl_add_u64 v[8:9], v[8:9], 0, s[18:19]
	s_or_saveexec_b64 s[8:9], s[8:9]
	v_ashrrev_i32_e32 v7, 31, v4
	s_xor_b64 exec, exec, s[8:9]
	v_lshlrev_b64 v[8:9], 11, v[10:11]
	v_lshl_add_u64 v[8:9], s[64:65], 0, v[8:9]
	v_mov_b32_e32 v5, v7
	v_lshl_add_u64 v[8:9], v[4:5], 1, v[8:9]
	s_or_b64 exec, exec, s[8:9]
	global_load_dwordx4 v[112:115], v[8:9], off
	v_add_u32_e32 v24, 0x200, v22
	v_mul_hi_i32 v0, v24, s20
	v_lshrrev_b32_e32 v5, 31, v0
	v_ashrrev_i32_e32 v0, 2, v0
	v_add_u32_e32 v8, v0, v5
	v_mul_lo_u32 v0, v8, 24
	v_sub_u32_e32 v5, v24, v0
	v_ashrrev_i32_e32 v9, 31, v8
	v_cmp_gt_i32_e64 s[8:9], 16, v5
	v_cmp_lt_i32_e32 vcc, 15, v5
	v_lshl_add_u64 v[16:17], s[60:61], 0, v[8:9]
	v_lshlrev_b32_e32 v10, 3, v5
	s_and_saveexec_b64 s[10:11], vcc
	s_xor_b64 s[10:11], exec, s[10:11]
	v_lshlrev_b64 v[14:15], 7, v[16:17]
	v_lshl_add_u64 v[14:15], s[14:15], 0, v[14:15]
	v_mov_b32_e32 v11, v1
	v_lshl_add_u64 v[14:15], v[10:11], 1, v[14:15]
	v_lshl_add_u64 v[14:15], v[14:15], 0, s[18:19]
	s_or_saveexec_b64 s[10:11], s[10:11]
	v_ashrrev_i32_e32 v13, 31, v10
	s_xor_b64 exec, exec, s[10:11]
	v_lshlrev_b64 v[14:15], 11, v[16:17]
	v_lshl_add_u64 v[14:15], s[64:65], 0, v[14:15]
	v_mov_b32_e32 v11, v13
	v_lshl_add_u64 v[14:15], v[10:11], 1, v[14:15]
	s_or_b64 exec, exec, s[10:11]
	global_load_dwordx4 v[116:119], v[14:15], off
	v_add_u32_e32 v0, 0x400, v22
	v_mul_hi_i32 v11, v0, s20
	v_lshrrev_b32_e32 v14, 31, v11
	v_ashrrev_i32_e32 v11, 2, v11
	v_add_u32_e32 v14, v11, v14
	v_mul_lo_u32 v11, v14, 24
	v_sub_u32_e32 v11, v0, v11
	v_ashrrev_i32_e32 v15, 31, v14
	v_cmp_gt_i32_e64 s[10:11], 16, v11
	v_cmp_lt_i32_e32 vcc, 15, v11
	v_lshl_add_u64 v[20:21], s[60:61], 0, v[14:15]
	v_lshlrev_b32_e32 v0, 3, v11
	s_and_saveexec_b64 s[34:35], vcc
	s_xor_b64 s[74:75], exec, s[34:35]
	v_lshlrev_b64 v[16:17], 7, v[20:21]
	v_lshl_add_u64 v[16:17], s[14:15], 0, v[16:17]
	v_lshl_add_u64 v[16:17], v[0:1], 1, v[16:17]
	v_lshl_add_u64 v[18:19], v[16:17], 0, s[18:19]
	s_or_saveexec_b64 s[74:75], s[74:75]
	v_mov_b64_e32 v[16:17], v[0:1]
	s_xor_b64 exec, exec, s[74:75]
	v_lshlrev_b64 v[16:17], 11, v[20:21]
	v_lshl_add_u64 v[18:19], s[64:65], 0, v[16:17]
	v_ashrrev_i32_e32 v17, 31, v0
	v_mov_b32_e32 v16, v0
	v_lshl_add_u64 v[18:19], v[16:17], 1, v[18:19]
	s_or_b64 exec, exec, s[74:75]
	global_load_dwordx4 v[120:123], v[18:19], off
	v_lshlrev_b32_e32 v18, 4, v22
	v_ashrrev_i32_e32 v26, 3, v22
	v_and_b32_e32 v18, 0x70, v18
	v_mov_b32_e32 v19, v1
	v_ashrrev_i32_e32 v27, 31, v26
	v_ashrrev_i32_e32 v24, 3, v24
	v_lshl_add_u64 v[20:21], s[62:63], 0, v[18:19]
	v_lshlrev_b64 v[28:29], 13, v[26:27]
	v_ashrrev_i32_e32 v25, 31, v24
	v_lshl_add_u64 v[30:31], v[20:21], 0, v[28:29]
	v_lshlrev_b64 v[32:33], 13, v[24:25]
	v_lshl_add_u64 v[20:21], v[20:21], 0, v[32:33]
	global_load_dwordx4 v[128:131], v[30:31], off
	global_load_dwordx4 v[124:127], v[20:21], off
	v_lshlrev_b32_e32 v34, 4, v12
	v_add_u32_e32 v25, 0, v18
	v_mad_u32_u24 v18, v6, s21, 0
	v_mul_i32_i24_e32 v6, 0xffffff00, v6
	v_and_b32_e32 v20, 7, v22
	v_lshl_add_u32 v241, v12, 4, v18
	v_add3_u32 v6, v18, v6, v34
	v_lshl_add_u64 v[18:19], s[66:67], 0, v[28:29]
	v_lshlrev_b32_e32 v20, 4, v20
	v_mov_b32_e32 v21, v1
	v_add_u32_e32 v239, 0x6400, v6
	v_add_u32_e32 v238, 0x7600, v6
	v_add_u32_e32 v237, 0x8800, v6
	v_add_u32_e32 v235, 0x9a00, v6
	v_mul_lo_u32 v6, v2, s21
	v_lshl_add_u64 v[132:133], v[18:19], 0, v[20:21]
	v_lshl_add_u64 v[18:19], s[66:67], 0, v[32:33]
	v_add_u32_e32 v27, 0, v6
	v_mul_lo_u32 v6, v8, s21
	v_lshl_add_u64 v[134:135], v[18:19], 0, v[20:21]
	v_lshlrev_b64 v[18:19], 7, v[2:3]
	v_lshlrev_b64 v[2:3], 11, v[2:3]
	v_add_u32_e32 v30, 0, v6
	v_mov_b32_e32 v6, v4
	v_lshl_add_u64 v[2:3], s[70:71], 0, v[2:3]
	v_lshl_add_u64 v[138:139], v[6:7], 1, v[2:3]
	v_lshlrev_b64 v[2:3], 7, v[8:9]
; #define LAS __attribute__((address_space(3)))
; __device__ __forceinline__ void attn_phase(LAS unsigned char* ldsb, bf16_t* P, const bf16_t* Kn, const bf16_t* KPE, const bf16_t* VT) {
;     ...
;             f32x16 o[4];
; #pragma unroll
;             for (int d = 0; d < 4; ++d) for (int i = 0; i < 16; ++i) o[d][i] = 0.f;
;             float mrun = -INFINITY, lrun = 0.f;
;             u32x4 kst[3], vst[2];
;     ...
;             ATT_LOAD(0);
;             for (int kt = 0; kt < nt; ++kt) {
;                 __syncthreads();
; #pragma unroll
;                 for (int i = 0; i < 3; ++i) { const int id = tid + 512 * i, row = id / 24, ch = id % 24; *(LAS u32x4*)(sK + row * 200 + ch * 8) = kst[i]; }
; #pragma unroll
;                 for (int i = 0; i < 2; ++i) { const int id = tid + 512 * i, d = id >> 3, ch = id & 7;
;                     *(LAS u32x2*)(sVt + d * 68 + ch * 8) = (u32x2){vst[i].x, vst[i].y}; *(LAS u32x2*)(sVt + d * 68 + ch * 8 + 4) = (u32x2){vst[i].z, vst[i].w}; }
;                 __syncthreads();
;                 if (kt + 1 < nt) ATT_LOAD(kt + 1);
	v_lshlrev_b32_e32 v35, 4, v11
	v_mov_b32_e32 v11, v1
	v_lshl_add_u64 v[2:3], s[68:69], 0, v[2:3]
	v_lshl_add_u64 v[140:141], v[10:11], 1, v[2:3]
	v_lshlrev_b64 v[2:3], 11, v[8:9]
	v_lshlrev_b32_e32 v229, 2, v12
	v_mov_b32_e32 v12, v10
	v_lshl_add_u64 v[2:3], s[70:71], 0, v[2:3]
	v_lshl_add_u64 v[142:143], v[12:13], 1, v[2:3]
	v_lshlrev_b64 v[2:3], 7, v[14:15]
	v_lshl_add_u64 v[2:3], s[68:69], 0, v[2:3]
	v_lshlrev_b32_e32 v31, 4, v5
	v_mul_lo_u32 v5, v14, s21
	v_lshl_add_u64 v[144:145], v[0:1], 1, v[2:3]
	v_lshlrev_b64 v[2:3], 11, v[14:15]
	s_addk_i32 s12, 0x100
	v_lshlrev_b32_e32 v23, 4, v23
	v_add_u32_e32 v34, 0, v5
	v_mul_lo_u32 v26, v26, s30
	v_mul_lo_u32 v24, v24, s30
	v_mov_b32_e32 v5, v1
	v_lshl_add_u64 v[18:19], s[68:69], 0, v[18:19]
	v_lshl_add_u64 v[2:3], s[70:71], 0, v[2:3]
	v_mov_b32_e32 v14, v1
	v_mov_b32_e32 v15, v1
	s_lshr_b32 s12, s12, 6
	v_lshl_add_u64 v[136:137], v[4:5], 1, v[18:19]
	v_lshl_add_u64 v[146:147], v[16:17], 1, v[2:3]
	v_mov_b32_e32 v0, v1
	v_mov_b32_e32 v2, v1
	v_mov_b32_e32 v3, v1
	v_mov_b32_e32 v4, v1
	v_mov_b32_e32 v6, v1
	v_mov_b32_e32 v7, v1
	v_mov_b32_e32 v8, v1
	v_mov_b32_e32 v9, v1
	v_mov_b32_e32 v10, v1
	v_mov_b32_e32 v12, v1
	v_mov_b32_e32 v13, v1
	v_add_u32_e32 v148, v27, v23
	v_add_u32_e32 v149, v30, v31
	v_add_u32_e32 v150, v34, v35
	v_add3_u32 v151, v25, v26, s29
	v_add3_u32 v152, v25, v24, s29
	v_and_b32_e32 v153, 1, v232
	v_lshlrev_b32_e32 v153, 3, v153
	v_sub_u32_e32 v151, v151, v153
	v_sub_u32_e32 v152, v152, v153
	v_mov_b64_e32 v[30:31], v[14:15]
	v_mov_b64_e32 v[46:47], v[14:15]
	v_mov_b64_e32 v[62:63], v[14:15]
	v_mov_b64_e32 v[78:79], v[14:15]
	s_xor_b64 s[74:75], s[76:77], -1
	s_or_b32 s76, s45, 31
	s_add_i32 s77, s12, -1
	v_mov_b32_e32 v240, 0xff800000
	v_mov_b32_e32 v236, 0
	s_mov_b32 s78, 63
	v_mov_b64_e32 v[28:29], v[12:13]
	v_mov_b64_e32 v[26:27], v[10:11]
	v_mov_b64_e32 v[24:25], v[8:9]
	v_mov_b64_e32 v[22:23], v[6:7]
	v_mov_b64_e32 v[20:21], v[4:5]
	v_mov_b64_e32 v[18:19], v[2:3]
	v_mov_b64_e32 v[16:17], v[0:1]
	v_mov_b64_e32 v[44:45], v[12:13]
	v_mov_b64_e32 v[42:43], v[10:11]
	v_mov_b64_e32 v[40:41], v[8:9]
	v_mov_b64_e32 v[38:39], v[6:7]
	v_mov_b64_e32 v[36:37], v[4:5]
	v_mov_b64_e32 v[34:35], v[2:3]
	v_mov_b64_e32 v[32:33], v[0:1]
	v_mov_b64_e32 v[60:61], v[12:13]
	v_mov_b64_e32 v[58:59], v[10:11]
	v_mov_b64_e32 v[56:57], v[8:9]
	v_mov_b64_e32 v[54:55], v[6:7]
	v_mov_b64_e32 v[52:53], v[4:5]
	v_mov_b64_e32 v[50:51], v[2:3]
	v_mov_b64_e32 v[48:49], v[0:1]
	v_mov_b64_e32 v[76:77], v[12:13]
	v_mov_b64_e32 v[74:75], v[10:11]
	v_mov_b64_e32 v[72:73], v[8:9]
	v_mov_b64_e32 v[70:71], v[6:7]
	v_mov_b64_e32 v[68:69], v[4:5]
	v_mov_b64_e32 v[66:67], v[2:3]
	v_mov_b64_e32 v[64:65], v[0:1]
	s_barrier
	s_waitcnt vmcnt(4)
	ds_write_b128 v148, v[112:115]
	s_waitcnt vmcnt(3)
	ds_write_b128 v149, v[116:119]
	s_waitcnt vmcnt(2)
	ds_write_b128 v150, v[120:123]
	s_waitcnt vmcnt(1)
	ds_write2_b64 v151, v[128:129], v[130:131] offset1:2
	s_waitcnt vmcnt(0)
	ds_write2_b64 v152, v[124:125], v[126:127] offset1:2
	v_cndmask_b32_e64 v2, v136, v138, s[6:7]
	v_cndmask_b32_e64 v3, v140, v142, s[8:9]
	v_cndmask_b32_e64 v4, v144, v146, s[10:11]
	s_waitcnt lgkmcnt(0)
	s_barrier
	global_load_dwordx4 v[112:115], v2, s[26:27]
	global_load_dwordx4 v[116:119], v3, s[26:27]
	global_load_dwordx4 v[120:123], v4, s[26:27]
	global_load_dwordx4 v[128:131], v132, s[26:27]
	global_load_dwordx4 v[124:127], v134, s[26:27]
	v_add_u32_e32 v132, 0x80, v132
	v_add_u32_e32 v134, 0x80, v134
	v_add_u32_e32 v136, 0x2000, v136
	v_add_u32_e32 v138, 0x20000, v138
	v_add_u32_e32 v140, 0x2000, v140
	v_add_u32_e32 v142, 0x20000, v142
	v_add_u32_e32 v144, 0x2000, v144
	v_add_u32_e32 v146, 0x20000, v146
	v_xor_b32_e32 v148, 0x10000, v148
	v_xor_b32_e32 v149, 0x10000, v149
	v_xor_b32_e32 v150, 0x10000, v150
	v_xor_b32_e32 v151, 0x10000, v151
	v_xor_b32_e32 v152, 0x10000, v152
	s_branch .LBB0_1527
; #define ATT_WV(n, x) asm volatile("s_waitcnt lgkmcnt(" #n ")" : "+v"(x) :: "memory")
; __device__ __forceinline__ void attn_phase(LAS unsigned char* ldsb, bf16_t* P, const bf16_t* Kn, const bf16_t* KPE, const bf16_t* VT) {
;     ...
;                     float ps = 0.f;
; #pragma unroll
;                     for (int kb = 0; kb < 2; ++kb)
; #pragma unroll
;                         for (int i = 0; i < 16; ++i) { const float p = __builtin_amdgcn_exp2f(st[kb][i] - mrun); st[kb][i] = p; ps += p; }
;                     lrun += ps;
;                     bf16x8 pb[2][2];
; #pragma unroll
;                     for (int kb = 0; kb < 2; ++kb)
; #pragma unroll
;                         for (int s2 = 0; s2 < 2; ++s2) {
;                             u32x4 pw; pw.x = pk2(st[kb][8 * s2 + 0], st[kb][8 * s2 + 1]); pw.y = pk2(st[kb][8 * s2 + 2], st[kb][8 * s2 + 3]);
;                             pw.z = pk2(st[kb][8 * s2 + 4], st[kb][8 * s2 + 5]); pw.w = pk2(st[kb][8 * s2 + 6], st[kb][8 * s2 + 7]);
;                             pb[kb][s2] = __builtin_bit_cast(bf16x8, pw); }
;                     {
;                         const unsigned va0 = (unsigned)(size_t)(sVt + r * 68 + 4 * hh), va1 = va0 + 32 * 68 * 2, va2 = va0 + 64 * 68 * 2, va3 = va0 + 96 * 68 * 2;
;                         bf16x8 vfa, vfb;
;     ...
;                         ATT_RV(vfa, va0, 0, 2);
;                         ATT_RV(vfb, va1, 0, 2); ATT_WV(1, vfa); o[0] = __builtin_amdgcn_mfma_f32_32x32x16_bf16(vfa, pb[0][0], o[0], 0, 0, 0);
;                         ATT_RV(vfa, va2, 0, 2); ATT_WV(1, vfb); o[1] = __builtin_amdgcn_mfma_f32_32x32x16_bf16(vfb, pb[0][0], o[1], 0, 0, 0);
;                         ATT_RV(vfb, va3, 0, 2); ATT_WV(1, vfa); o[2] = __builtin_amdgcn_mfma_f32_32x32x16_bf16(vfa, pb[0][0], o[2], 0, 0, 0);
;                         ATT_RV(vfa, va0, 4, 6); ATT_WV(1, vfb); o[3] = __builtin_amdgcn_mfma_f32_32x32x16_bf16(vfb, pb[0][0], o[3], 0, 0, 0);
;                         ATT_RV(vfb, va1, 4, 6); ATT_WV(1, vfa); o[0] = __builtin_amdgcn_mfma_f32_32x32x16_bf16(vfa, pb[0][1], o[0], 0, 0, 0);
;                         ATT_RV(vfa, va2, 4, 6); ATT_WV(1, vfb); o[1] = __builtin_amdgcn_mfma_f32_32x32x16_bf16(vfb, pb[0][1], o[1], 0, 0, 0);
;                         ATT_RV(vfb, va3, 4, 6); ATT_WV(1, vfa); o[2] = __builtin_amdgcn_mfma_f32_32x32x16_bf16(vfa, pb[0][1], o[2], 0, 0, 0);
.LBB0_1525:
	v_sub_f32_e32 v96, v96, v240
	v_sub_f32_e32 v97, v97, v240
	v_exp_f32_e32 v96, v96
	v_sub_f32_e32 v98, v98, v240
	v_exp_f32_e32 v97, v97
	v_sub_f32_e32 v99, v99, v240
	v_exp_f32_e32 v98, v98
	v_add_f32_e32 v0, 0, v96
	v_exp_f32_e32 v99, v99
	v_sub_f32_e32 v100, v100, v240
	v_add_f32_e32 v0, v97, v0
	v_sub_f32_e32 v101, v101, v240
	v_exp_f32_e32 v100, v100
	v_cvt_pk_bf16_f32 v2, v96, v97
	v_add_f32_e32 v0, v98, v0
	v_exp_f32_e32 v101, v101
	v_sub_f32_e32 v102, v102, v240
	v_add_f32_e32 v0, v99, v0
	v_sub_f32_e32 v103, v103, v240
	v_exp_f32_e32 v102, v102
	v_cvt_pk_bf16_f32 v3, v98, v99
	v_exp_f32_e32 v103, v103
	v_add_f32_e32 v0, v100, v0
	v_add_f32_e32 v0, v101, v0
	v_cvt_pk_bf16_f32 v4, v100, v101
	v_add_f32_e32 v0, v102, v0
	v_cvt_pk_bf16_f32 v5, v102, v103
	v_add_f32_e32 v0, v103, v0
	s_waitcnt lgkmcnt(7)
	v_mfma_f32_32x32x16_bf16 v[64:79], v[154:157], v[2:5], v[64:79]
	ds_read_b128 v[154:157], v239 offset:64
	v_sub_f32_e32 v104, v104, v240
	v_sub_f32_e32 v105, v105, v240
	v_exp_f32_e32 v104, v104
	v_sub_f32_e32 v106, v106, v240
	v_exp_f32_e32 v105, v105
	v_sub_f32_e32 v107, v107, v240
	v_exp_f32_e32 v106, v106
	s_waitcnt lgkmcnt(7)
	v_mfma_f32_32x32x16_bf16 v[48:63], v[158:161], v[2:5], v[48:63]
	ds_read_b128 v[158:161], v238 offset:64
	v_add_f32_e32 v0, v104, v0
	v_exp_f32_e32 v107, v107
	v_sub_f32_e32 v108, v108, v240
	v_add_f32_e32 v0, v105, v0
	v_sub_f32_e32 v109, v109, v240
	v_exp_f32_e32 v108, v108
	v_cvt_pk_bf16_f32 v6, v104, v105
	s_waitcnt lgkmcnt(7)
	v_mfma_f32_32x32x16_bf16 v[32:47], v[162:165], v[2:5], v[32:47]
	ds_read_b128 v[162:165], v237 offset:64
	v_add_f32_e32 v0, v106, v0
	v_exp_f32_e32 v109, v109
	v_sub_f32_e32 v110, v110, v240
	v_add_f32_e32 v0, v107, v0
	v_sub_f32_e32 v111, v111, v240
	v_exp_f32_e32 v110, v110
	v_cvt_pk_bf16_f32 v7, v106, v107
	s_waitcnt lgkmcnt(7)
	v_mfma_f32_32x32x16_bf16 v[16:31], v[166:169], v[2:5], v[16:31]
	ds_read_b128 v[166:169], v235 offset:64
	v_exp_f32_e32 v111, v111
	v_add_f32_e32 v0, v108, v0
	v_add_f32_e32 v0, v109, v0
	v_cvt_pk_bf16_f32 v8, v108, v109
	v_add_f32_e32 v0, v110, v0
	v_cvt_pk_bf16_f32 v9, v110, v111
	v_add_f32_e32 v0, v111, v0
	s_waitcnt lgkmcnt(7)
	v_mfma_f32_32x32x16_bf16 v[64:79], v[170:173], v[6:9], v[64:79]
	ds_read_b128 v[170:173], v239 offset:96
	v_sub_f32_e32 v80, v80, v240
	v_sub_f32_e32 v81, v81, v240
	v_exp_f32_e32 v80, v80
	v_sub_f32_e32 v82, v82, v240
	v_exp_f32_e32 v81, v81
	v_sub_f32_e32 v83, v83, v240
	v_exp_f32_e32 v82, v82
	s_waitcnt lgkmcnt(7)
	v_mfma_f32_32x32x16_bf16 v[48:63], v[244:247], v[6:9], v[48:63]
	ds_read_b128 v[244:247], v238 offset:96
	v_add_f32_e32 v0, v80, v0
	v_exp_f32_e32 v83, v83
	v_sub_f32_e32 v84, v84, v240
	v_add_f32_e32 v0, v81, v0
	v_sub_f32_e32 v85, v85, v240
	v_exp_f32_e32 v84, v84
	v_cvt_pk_bf16_f32 v10, v80, v81
	s_waitcnt lgkmcnt(7)
	v_mfma_f32_32x32x16_bf16 v[32:47], v[248:251], v[6:9], v[32:47]
	ds_read_b128 v[248:251], v237 offset:96
	v_add_f32_e32 v0, v82, v0
	v_exp_f32_e32 v85, v85
	v_sub_f32_e32 v86, v86, v240
	v_add_f32_e32 v0, v83, v0
	v_sub_f32_e32 v87, v87, v240
	v_exp_f32_e32 v86, v86
	v_cvt_pk_bf16_f32 v11, v82, v83
	s_waitcnt lgkmcnt(7)
	v_mfma_f32_32x32x16_bf16 v[16:31], v[252:255], v[6:9], v[16:31]
	ds_read_b128 v[252:255], v235 offset:96
	v_exp_f32_e32 v87, v87
	v_add_f32_e32 v0, v84, v0
	v_add_f32_e32 v0, v85, v0
	v_cvt_pk_bf16_f32 v12, v84, v85
	v_add_f32_e32 v0, v86, v0
	v_cvt_pk_bf16_f32 v13, v86, v87
	v_add_f32_e32 v0, v87, v0
	s_waitcnt lgkmcnt(7)
	v_mfma_f32_32x32x16_bf16 v[64:79], v[154:157], v[10:13], v[64:79]
	v_sub_f32_e32 v88, v88, v240
	v_sub_f32_e32 v89, v89, v240
	v_exp_f32_e32 v88, v88
	v_sub_f32_e32 v90, v90, v240
	v_exp_f32_e32 v89, v89
	v_sub_f32_e32 v91, v91, v240
	v_exp_f32_e32 v90, v90
	s_waitcnt lgkmcnt(6)
	v_mfma_f32_32x32x16_bf16 v[48:63], v[158:161], v[10:13], v[48:63]
	v_add_f32_e32 v0, v88, v0
	v_exp_f32_e32 v91, v91
	v_sub_f32_e32 v92, v92, v240
	v_add_f32_e32 v0, v89, v0
	v_sub_f32_e32 v93, v93, v240
	v_exp_f32_e32 v92, v92
	v_cvt_pk_bf16_f32 v96, v88, v89
	s_waitcnt lgkmcnt(5)
	v_mfma_f32_32x32x16_bf16 v[32:47], v[162:165], v[10:13], v[32:47]
	v_add_f32_e32 v0, v90, v0
	v_exp_f32_e32 v93, v93
	v_sub_f32_e32 v94, v94, v240
	v_add_f32_e32 v0, v91, v0
	v_sub_f32_e32 v95, v95, v240
	v_exp_f32_e32 v94, v94
	v_cvt_pk_bf16_f32 v97, v90, v91
	s_waitcnt lgkmcnt(4)
	v_mfma_f32_32x32x16_bf16 v[16:31], v[166:169], v[10:13], v[16:31]
	v_exp_f32_e32 v95, v95
	v_add_f32_e32 v0, v92, v0
	v_add_f32_e32 v0, v93, v0
	v_cvt_pk_bf16_f32 v98, v92, v93
	v_add_f32_e32 v0, v94, v0
	v_cvt_pk_bf16_f32 v99, v94, v95
	v_add_f32_e32 v0, v95, v0
	s_waitcnt lgkmcnt(3)
	v_mfma_f32_32x32x16_bf16 v[64:79], v[170:173], v[96:99], v[64:79]
	v_add_f32_e32 v236, v236, v0
	s_waitcnt lgkmcnt(2)
	v_mfma_f32_32x32x16_bf16 v[48:63], v[244:247], v[96:99], v[48:63]
	s_waitcnt lgkmcnt(1)
	v_mfma_f32_32x32x16_bf16 v[32:47], v[248:251], v[96:99], v[32:47]
	s_waitcnt lgkmcnt(0)
	v_mfma_f32_32x32x16_bf16 v[16:31], v[252:255], v[96:99], v[16:31]

; #define LAS __attribute__((address_space(3)))
; __device__ __forceinline__ void attn_phase(LAS unsigned char* ldsb, bf16_t* P, const bf16_t* Kn, const bf16_t* KPE, const bf16_t* VT) {
;     ...
;             for (int kt = 0; kt < nt; ++kt) {
;                 __syncthreads();
; #pragma unroll
;                 for (int i = 0; i < 3; ++i) { const int id = tid + 512 * i, row = id / 24, ch = id % 24; *(LAS u32x4*)(sK + row * 200 + ch * 8) = kst[i]; }
; #pragma unroll
;                 for (int i = 0; i < 2; ++i) { const int id = tid + 512 * i, d = id >> 3, ch = id & 7;
;                     *(LAS u32x2*)(sVt + d * 68 + ch * 8) = (u32x2){vst[i].x, vst[i].y}; *(LAS u32x2*)(sVt + d * 68 + ch * 8 + 4) = (u32x2){vst[i].z, vst[i].w}; }
;                 __syncthreads();
;                 if (kt + 1 < nt) ATT_LOAD(kt + 1);
.LBB0_1527:
	s_cmp_lt_u32 s77, 2
	s_cbranch_scc1 .Lattn_nopre
	s_waitcnt vmcnt(4)
	ds_write_b128 v148, v[112:115]
	s_waitcnt vmcnt(3)
	ds_write_b128 v149, v[116:119]
	s_waitcnt vmcnt(2)
	ds_write_b128 v150, v[120:123]
	s_waitcnt vmcnt(1)
	ds_write2_b64 v151, v[128:129], v[130:131] offset1:2
	s_waitcnt vmcnt(0)
	ds_write2_b64 v152, v[124:125], v[126:127] offset1:2
	v_cndmask_b32_e64 v2, v136, v138, s[6:7]
	v_cndmask_b32_e64 v3, v140, v142, s[8:9]
	v_cndmask_b32_e64 v4, v144, v146, s[10:11]
	s_waitcnt lgkmcnt(0)
	global_load_dwordx4 v[112:115], v2, s[26:27]
	global_load_dwordx4 v[116:119], v3, s[26:27]
	global_load_dwordx4 v[120:123], v4, s[26:27]
	global_load_dwordx4 v[128:131], v132, s[26:27]
	global_load_dwordx4 v[124:127], v134, s[26:27]
	v_add_u32_e32 v132, 0x80, v132
	v_add_u32_e32 v134, 0x80, v134
	v_add_u32_e32 v136, 0x2000, v136
	v_add_u32_e32 v138, 0x20000, v138
	v_add_u32_e32 v140, 0x2000, v140
	v_add_u32_e32 v142, 0x20000, v142
	v_add_u32_e32 v144, 0x2000, v144
	v_add_u32_e32 v146, 0x20000, v146

; DI unsigned pk2(float a, float b) { f32x2 v = {a, b}; bf16v2 r = __builtin_convertvector(v, bf16v2); return __builtin_bit_cast(unsigned, r); }
; #define ATT_RV(dst, va, o0, o1) asm volatile("ds_read2_b64 %0, %1 offset0:" #o0 " offset1:" #o1 : "=&v"(dst) : "v"(va) : "memory")
; __device__ __forceinline__ void attn_phase(LAS unsigned char* ldsb, bf16_t* P, const bf16_t* Kn, const bf16_t* KPE, const bf16_t* VT) {
;     ...
;                     float mx = st[0][0];
; #pragma unroll
;                     for (int kb = 0; kb < 2; ++kb)
; #pragma unroll
;                         for (int i = 0; i < 16; ++i) mx = fmaxf(mx, st[kb][i]);
;                     mx = fmaxf(mx, __shfl_xor(mx, 32));
;                     if (__builtin_amdgcn_ballot_w64(mx > mrun) != 0ull) {
;                         const float mnew = fmaxf(mrun, mx);
;                         const float alpha = __builtin_amdgcn_exp2f(mrun - mnew);
;                         mrun = mnew; lrun *= alpha;
; #pragma unroll
;                         for (int d = 0; d < 4; ++d)
; #pragma unroll
;                             for (int i = 0; i < 16; ++i) o[d][i] *= alpha;
;                     }
;                     float ps = 0.f;
; #pragma unroll
;                     for (int kb = 0; kb < 2; ++kb)
; #pragma unroll
;                         for (int i = 0; i < 16; ++i) { const float p = __builtin_amdgcn_exp2f(st[kb][i] - mrun); st[kb][i] = p; ps += p; }
;                     lrun += ps;
;                     bf16x8 pb[2][2];
; #pragma unroll
;                     for (int kb = 0; kb < 2; ++kb)
; #pragma unroll
;                         for (int s2 = 0; s2 < 2; ++s2) {
;                             u32x4 pw; pw.x = pk2(st[kb][8 * s2 + 0], st[kb][8 * s2 + 1]); pw.y = pk2(st[kb][8 * s2 + 2], st[kb][8 * s2 + 3]);
;                             pw.z = pk2(st[kb][8 * s2 + 4], st[kb][8 * s2 + 5]); pw.w = pk2(st[kb][8 * s2 + 6], st[kb][8 * s2 + 7]);
;                             pb[kb][s2] = __builtin_bit_cast(bf16x8, pw); }
;                     {
;                         const unsigned va0 = (unsigned)(size_t)(sVt + r * 68 + 4 * hh), va1 = va0 + 32 * 68 * 2, va2 = va0 + 64 * 68 * 2, va3 = va0 + 96 * 68 * 2;
;                         bf16x8 vfa, vfb;
;     ...
;                         ATT_RV(vfa, va0, 0, 2);
.LBB0_1530:
	ds_read_b128 v[154:157], v239 offset:0
	ds_read_b128 v[158:161], v238 offset:0
	ds_read_b128 v[162:165], v237 offset:0
	ds_read_b128 v[166:169], v235 offset:0
	ds_read_b128 v[170:173], v239 offset:32
	ds_read_b128 v[244:247], v238 offset:32
	ds_read_b128 v[248:251], v237 offset:32
	ds_read_b128 v[252:255], v235 offset:32
	s_nop 1
	v_max_f32_e32 v0, v97, v97
	v_max_f32_e32 v2, v96, v96
	v_max_f32_e32 v0, v2, v0
	v_max3_f32 v0, v0, v98, v99
	v_max3_f32 v0, v0, v100, v101
	v_max3_f32 v0, v0, v102, v103
	v_max3_f32 v0, v0, v104, v105
	v_max3_f32 v0, v0, v106, v107
	v_max3_f32 v0, v0, v108, v109
	v_max3_f32 v0, v0, v110, v111
	v_max3_f32 v0, v0, v80, v81
	v_max3_f32 v0, v0, v82, v83
	v_max3_f32 v0, v0, v84, v85
	v_max3_f32 v0, v0, v86, v87
	v_and_b32_e32 v3, 64, v234
	v_max3_f32 v0, v0, v88, v89
	v_xor_b32_e32 v2, 32, v234
	v_add_u32_e32 v3, 64, v3
	v_max3_f32 v0, v0, v90, v91
	v_cmp_lt_i32_e32 vcc, v2, v3
	v_max3_f32 v0, v0, v92, v93
	v_max3_f32 v0, v0, v94, v95
	v_cndmask_b32_e32 v2, v234, v2, vcc
	v_lshlrev_b32_e32 v2, 2, v2
	ds_bpermute_b32 v2, v2, v0
	s_waitcnt lgkmcnt(0)
	v_max_f32_e32 v2, v2, v2
	v_max_f32_e32 v0, v0, v2
	v_sub_f32_e32 v2, v0, v240
	v_cmp_lt_f32_e32 vcc, 4.0, v2
	s_cbranch_vccz .LBB0_1525
	v_max_f32_e32 v0, v0, v0
	v_max_f32_e32 v2, v240, v240
	v_max_f32_e32 v2, v2, v0
	v_sub_f32_e32 v0, v240, v2
	v_exp_f32_e32 v0, v0
	v_mov_b32_e32 v240, v2
	v_pk_mul_f32 v[78:79], v[78:79], v[0:1] op_sel_hi:[1,0]
	v_pk_mul_f32 v[76:77], v[76:77], v[0:1] op_sel_hi:[1,0]
	v_pk_mul_f32 v[74:75], v[74:75], v[0:1] op_sel_hi:[1,0]
	v_pk_mul_f32 v[72:73], v[72:73], v[0:1] op_sel_hi:[1,0]
	v_pk_mul_f32 v[70:71], v[70:71], v[0:1] op_sel_hi:[1,0]
	v_pk_mul_f32 v[68:69], v[68:69], v[0:1] op_sel_hi:[1,0]
	v_pk_mul_f32 v[66:67], v[66:67], v[0:1] op_sel_hi:[1,0]
	v_pk_mul_f32 v[64:65], v[64:65], v[0:1] op_sel_hi:[1,0]
	v_pk_mul_f32 v[62:63], v[62:63], v[0:1] op_sel_hi:[1,0]
	v_pk_mul_f32 v[60:61], v[60:61], v[0:1] op_sel_hi:[1,0]
	v_pk_mul_f32 v[58:59], v[58:59], v[0:1] op_sel_hi:[1,0]
	v_pk_mul_f32 v[56:57], v[56:57], v[0:1] op_sel_hi:[1,0]
	v_pk_mul_f32 v[54:55], v[54:55], v[0:1] op_sel_hi:[1,0]
	v_pk_mul_f32 v[52:53], v[52:53], v[0:1] op_sel_hi:[1,0]
	v_pk_mul_f32 v[50:51], v[50:51], v[0:1] op_sel_hi:[1,0]
	v_pk_mul_f32 v[48:49], v[48:49], v[0:1] op_sel_hi:[1,0]
	v_pk_mul_f32 v[46:47], v[46:47], v[0:1] op_sel_hi:[1,0]
	v_pk_mul_f32 v[44:45], v[44:45], v[0:1] op_sel_hi:[1,0]
	v_pk_mul_f32 v[42:43], v[42:43], v[0:1] op_sel_hi:[1,0]
	v_pk_mul_f32 v[40:41], v[40:41], v[0:1] op_sel_hi:[1,0]
	v_pk_mul_f32 v[38:39], v[38:39], v[0:1] op_sel_hi:[1,0]
	v_pk_mul_f32 v[36:37], v[36:37], v[0:1] op_sel_hi:[1,0]
	v_pk_mul_f32 v[34:35], v[34:35], v[0:1] op_sel_hi:[1,0]
	v_pk_mul_f32 v[32:33], v[32:33], v[0:1] op_sel_hi:[1,0]
	v_pk_mul_f32 v[30:31], v[30:31], v[0:1] op_sel_hi:[1,0]
	v_pk_mul_f32 v[28:29], v[28:29], v[0:1] op_sel_hi:[1,0]
	v_pk_mul_f32 v[26:27], v[26:27], v[0:1] op_sel_hi:[1,0]
	v_pk_mul_f32 v[24:25], v[24:25], v[0:1] op_sel_hi:[1,0]
	v_pk_mul_f32 v[22:23], v[22:23], v[0:1] op_sel_hi:[1,0]
	v_pk_mul_f32 v[20:21], v[20:21], v[0:1] op_sel_hi:[1,0]
	v_pk_mul_f32 v[18:19], v[18:19], v[0:1] op_sel_hi:[1,0]
	v_pk_mul_f32 v[16:17], v[16:17], v[0:1] op_sel_hi:[1,0]
	v_mul_f32_e32 v236, v236, v0
	s_branch .LBB0_1525
; #define LAS __attribute__((address_space(3)))
; __device__ __forceinline__ void attn_phase(LAS unsigned char* ldsb, bf16_t* P, const bf16_t* Kn, const bf16_t* KPE, const bf16_t* VT) {
;     ...
;             for (int kt = 0; kt < nt; ++kt) {
;                 __syncthreads();
; #pragma unroll
;                 for (int i = 0; i < 3; ++i) { const int id = tid + 512 * i, row = id / 24, ch = id % 24; *(LAS u32x4*)(sK + row * 200 + ch * 8) = kst[i]; }
; #pragma unroll
;                 for (int i = 0; i < 2; ++i) { const int id = tid + 512 * i, d = id >> 3, ch = id & 7;
;                     *(LAS u32x2*)(sVt + d * 68 + ch * 8) = (u32x2){vst[i].x, vst[i].y}; *(LAS u32x2*)(sVt + d * 68 + ch * 8 + 4) = (u32x2){vst[i].z, vst[i].w}; }
;                 __syncthreads();
;                 if (kt + 1 < nt) ATT_LOAD(kt + 1);
;                 const int k0 = kt * 64;
;                 if (k0 <= q0 + w * 32 + 31) {
;                     f32x16 st[2];
; #pragma unroll
;                     for (int kb = 0; kb < 2; ++kb) for (int i = 0; i < 16; ++i) st[kb][i] = 0.f;
;                     {
;                         const unsigned kaddr = (unsigned)(size_t)(sK + r * 200 + hh * 8);
;                         bf16x8 ka0, ka1, kb0, kb1;
;     ...
;                         ATT_RD(ka0, 0);   ATT_RD(ka1, 12800);
;                         ATT_RD(kb0, 32);  ATT_RD(kb1, 12832);  ATT_WT(2, ka0, ka1); ATT_MM(ka0, ka1, 0);
;                         ATT_RD(ka0, 64);  ATT_RD(ka1, 12864);  ATT_WT(2, kb0, kb1); ATT_MM(kb0, kb1, 1);
;                         ATT_RD(kb0, 96);  ATT_RD(kb1, 12896);  ATT_WT(2, ka0, ka1); ATT_MM(ka0, ka1, 2);
;                         ATT_RD(ka0, 128); ATT_RD(ka1, 12928);  ATT_WT(2, kb0, kb1); ATT_MM(kb0, kb1, 3);
;                         ATT_RD(kb0, 160); ATT_RD(kb1, 12960);  ATT_WT(2, ka0, ka1); ATT_MM(ka0, ka1, 4);
;                         ATT_RD(ka0, 192); ATT_RD(ka1, 12992);  ATT_WT(2, kb0, kb1); ATT_MM(kb0, kb1, 5);
;                         ATT_RD(kb0, 224); ATT_RD(kb1, 13024);  ATT_WT(2, ka0, ka1); ATT_MM(ka0, ka1, 6);
;                         ATT_RD(ka0, 256); ATT_RD(ka1, 13056);  ATT_WT(2, kb0, kb1); ATT_MM(kb0, kb1, 7);
;                         ATT_RD(kb0, 288); ATT_RD(kb1, 13088);  ATT_WT(2, ka0, ka1); ATT_MM(ka0, ka1, 8);
;                         ATT_RD(ka0, 320); ATT_RD(ka1, 13120);  ATT_WT(2, kb0, kb1); ATT_MM(kb0, kb1, 9);
.LBB0_1532:
	s_sub_i32 s8, s78, 63
	s_cmp_le_i32 s8, s76
	s_mov_b64 s[6:7], -1
	s_barrier
	s_waitcnt vmcnt(4)
	ds_write_b128 v148, v[112:115]
	s_waitcnt vmcnt(3)
	ds_write_b128 v149, v[116:119]
	s_waitcnt vmcnt(2)
	ds_write_b128 v150, v[120:123]
	s_waitcnt vmcnt(1)
	ds_write2_b64 v151, v[128:129], v[130:131] offset1:2
	s_waitcnt vmcnt(0)
	ds_write2_b64 v152, v[124:125], v[126:127] offset1:2
	s_waitcnt lgkmcnt(0)
	s_barrier
	s_cbranch_scc0 .LBB0_1539
	ds_read_b128 v[2:5], v241 offset:0
	ds_read_b128 v[6:9], v241 offset:12800
	ds_read_b128 v[10:13], v241 offset:32
	ds_read_b128 v[112:115], v241 offset:12832
	s_or_b32 s6, s8, 63
	s_waitcnt lgkmcnt(2)
	s_cmp_le_i32 s6, s45
	v_mfma_f32_32x32x16_bf16 v[96:111], v[2:5], v[220:223], 0
	ds_read_b128 v[2:5], v241 offset:64
	v_mfma_f32_32x32x16_bf16 v[80:95], v[6:9], v[220:223], 0
	ds_read_b128 v[6:9], v241 offset:12864
	s_waitcnt lgkmcnt(2)
	s_nop 0
	v_mfma_f32_32x32x16_bf16 v[96:111], v[10:13], v[216:219], v[96:111]
	ds_read_b128 v[10:13], v241 offset:96
	v_mfma_f32_32x32x16_bf16 v[80:95], v[112:115], v[216:219], v[80:95]
	ds_read_b128 v[112:115], v241 offset:12896
	s_waitcnt lgkmcnt(2)
	s_nop 0
	v_mfma_f32_32x32x16_bf16 v[96:111], v[2:5], v[212:215], v[96:111]
	ds_read_b128 v[2:5], v241 offset:128
	v_mfma_f32_32x32x16_bf16 v[80:95], v[6:9], v[212:215], v[80:95]
	ds_read_b128 v[6:9], v241 offset:12928
	s_waitcnt lgkmcnt(2)
	s_nop 0
	v_mfma_f32_32x32x16_bf16 v[96:111], v[10:13], v[208:211], v[96:111]
	ds_read_b128 v[10:13], v241 offset:160
	v_mfma_f32_32x32x16_bf16 v[80:95], v[112:115], v[208:211], v[80:95]
	ds_read_b128 v[112:115], v241 offset:12960
	s_waitcnt lgkmcnt(2)
	s_nop 0
	v_mfma_f32_32x32x16_bf16 v[96:111], v[2:5], v[204:207], v[96:111]
	ds_read_b128 v[2:5], v241 offset:192
	v_mfma_f32_32x32x16_bf16 v[80:95], v[6:9], v[204:207], v[80:95]
	ds_read_b128 v[6:9], v241 offset:12992
	s_waitcnt lgkmcnt(2)
	s_nop 0
	v_mfma_f32_32x32x16_bf16 v[96:111], v[10:13], v[200:203], v[96:111]
	ds_read_b128 v[10:13], v241 offset:224
	v_mfma_f32_32x32x16_bf16 v[80:95], v[112:115], v[200:203], v[80:95]
	ds_read_b128 v[112:115], v241 offset:13024
	s_waitcnt lgkmcnt(2)
	s_nop 0
	v_mfma_f32_32x32x16_bf16 v[96:111], v[2:5], v[196:199], v[96:111]
	ds_read_b128 v[2:5], v241 offset:256
	v_mfma_f32_32x32x16_bf16 v[80:95], v[6:9], v[196:199], v[80:95]
	ds_read_b128 v[6:9], v241 offset:13056
	s_waitcnt lgkmcnt(2)
	s_nop 0
	v_mfma_f32_32x32x16_bf16 v[96:111], v[10:13], v[192:195], v[96:111]
	ds_read_b128 v[10:13], v241 offset:288
	v_mfma_f32_32x32x16_bf16 v[80:95], v[112:115], v[192:195], v[80:95]
	ds_read_b128 v[112:115], v241 offset:13088
	s_waitcnt lgkmcnt(2)
	s_nop 0
	v_mfma_f32_32x32x16_bf16 v[96:111], v[2:5], v[188:191], v[96:111]
	ds_read_b128 v[2:5], v241 offset:320
	v_mfma_f32_32x32x16_bf16 v[80:95], v[6:9], v[188:191], v[80:95]
	ds_read_b128 v[6:9], v241 offset:13120
	s_waitcnt lgkmcnt(2)
	s_nop 0
	v_mfma_f32_32x32x16_bf16 v[96:111], v[10:13], v[184:187], v[96:111]
	ds_read_b128 v[10:13], v241 offset:352
	v_mfma_f32_32x32x16_bf16 v[80:95], v[112:115], v[184:187], v[80:95]
	ds_read_b128 v[112:115], v241 offset:13152
	s_waitcnt lgkmcnt(2)
	s_nop 0
	s_waitcnt lgkmcnt(0)
	v_mfma_f32_32x32x16_bf16 v[96:111], v[2:5], v[180:183], v[96:111]
	v_mfma_f32_32x32x16_bf16 v[80:95], v[6:9], v[180:183], v[80:95]
	v_mfma_f32_32x32x16_bf16 v[96:111], v[10:13], v[176:179], v[96:111]
	v_mfma_f32_32x32x16_bf16 v[80:95], v[112:115], v[176:179], v[80:95]
	s_cbranch_scc1 .LBB0_1535
	v_or_b32_e32 v0, s8, v229
	v_cmp_gt_i32_e32 vcc, v0, v228
	s_nop 7
	v_cndmask_b32_e32 v2, v96, v233, vcc
	v_cmp_lt_i32_e32 vcc, v0, v228
	s_nop 1
	v_cndmask_b32_e32 v96, v2, v96, vcc
	v_or_b32_e32 v2, 2, v0
	v_cndmask_b32_e32 v97, v233, v97, vcc
	v_cmp_le_i32_e32 vcc, v2, v228
	v_or_b32_e32 v2, 3, v0
	s_nop 0
	v_cndmask_b32_e32 v98, v233, v98, vcc
	v_cmp_le_i32_e32 vcc, v2, v228
	v_or_b32_e32 v2, 8, v0
	s_nop 0
	v_cndmask_b32_e32 v99, v233, v99, vcc
	v_cmp_le_i32_e32 vcc, v2, v228
	v_or_b32_e32 v2, 9, v0
	s_nop 0
	v_cndmask_b32_e32 v100, v233, v100, vcc
	v_cmp_le_i32_e32 vcc, v2, v228
	v_or_b32_e32 v2, 10, v0
	s_nop 0
	v_cndmask_b32_e32 v101, v233, v101, vcc
	v_cmp_le_i32_e32 vcc, v2, v228
	v_or_b32_e32 v2, 11, v0
	s_nop 0
	v_cndmask_b32_e32 v102, v233, v102, vcc
	v_cmp_le_i32_e32 vcc, v2, v228
	v_or_b32_e32 v2, 16, v0
	s_nop 0
	v_cndmask_b32_e32 v103, v233, v103, vcc
	v_cmp_le_i32_e32 vcc, v2, v228
	v_or_b32_e32 v2, 17, v0
	s_nop 0
	v_cndmask_b32_e32 v104, v233, v104, vcc
	v_cmp_le_i32_e32 vcc, v2, v228
	v_or_b32_e32 v2, 18, v0
	s_nop 0
	v_cndmask_b32_e32 v105, v233, v105, vcc
	v_cmp_le_i32_e32 vcc, v2, v228
	v_or_b32_e32 v2, 19, v0
	s_nop 0
	v_cndmask_b32_e32 v106, v233, v106, vcc
	v_cmp_le_i32_e32 vcc, v2, v228
	v_or_b32_e32 v2, 24, v0
	s_nop 0
	v_cndmask_b32_e32 v107, v233, v107, vcc
	v_cmp_le_i32_e32 vcc, v2, v228
	v_or_b32_e32 v2, 25, v0
	s_nop 0
	v_cndmask_b32_e32 v108, v233, v108, vcc
	v_cmp_le_i32_e32 vcc, v2, v228
	v_or_b32_e32 v2, 26, v0
	s_nop 0
	v_cndmask_b32_e32 v109, v233, v109, vcc
	v_cmp_le_i32_e32 vcc, v2, v228
	v_or_b32_e32 v2, 27, v0
	s_nop 0
	v_cndmask_b32_e32 v110, v233, v110, vcc
	v_cmp_le_i32_e32 vcc, v2, v228
	v_or_b32_e32 v2, 32, v0
	s_nop 0
	v_cndmask_b32_e32 v111, v233, v111, vcc
	v_cmp_le_i32_e32 vcc, v2, v228
	v_or_b32_e32 v2, 33, v0
	s_nop 0
	v_cndmask_b32_e32 v80, v233, v80, vcc
	v_cmp_le_i32_e32 vcc, v2, v228
	v_or_b32_e32 v2, 34, v0
	s_nop 0
	v_cndmask_b32_e32 v81, v233, v81, vcc
	v_cmp_le_i32_e32 vcc, v2, v228
	v_or_b32_e32 v2, 35, v0
	s_nop 0
	v_cndmask_b32_e32 v82, v233, v82, vcc
	v_cmp_le_i32_e32 vcc, v2, v228
	v_or_b32_e32 v2, 40, v0
	s_nop 0
	v_cndmask_b32_e32 v83, v233, v83, vcc
	v_cmp_le_i32_e32 vcc, v2, v228
	v_or_b32_e32 v2, 41, v0
	s_nop 0
	v_cndmask_b32_e32 v84, v233, v84, vcc
	v_cmp_le_i32_e32 vcc, v2, v228
	v_or_b32_e32 v2, 42, v0
	s_nop 0
	v_cndmask_b32_e32 v85, v233, v85, vcc
	v_cmp_le_i32_e32 vcc, v2, v228
	v_or_b32_e32 v2, 43, v0
	s_nop 0
	v_cndmask_b32_e32 v86, v233, v86, vcc
	v_cmp_le_i32_e32 vcc, v2, v228
	v_or_b32_e32 v2, 48, v0
	s_nop 0
	v_cndmask_b32_e32 v87, v233, v87, vcc
	v_cmp_le_i32_e32 vcc, v2, v228
	v_or_b32_e32 v2, 49, v0
	s_nop 0
	v_cndmask_b32_e32 v88, v233, v88, vcc
	v_cmp_le_i32_e32 vcc, v2, v228
	v_or_b32_e32 v2, 50, v0
	s_nop 0
	v_cndmask_b32_e32 v89, v233, v89, vcc
	v_cmp_le_i32_e32 vcc, v2, v228
	v_or_b32_e32 v2, 51, v0
	s_nop 0
	v_cndmask_b32_e32 v90, v233, v90, vcc
	v_cmp_le_i32_e32 vcc, v2, v228
	v_or_b32_e32 v2, 56, v0
	s_nop 0
	v_cndmask_b32_e32 v91, v233, v91, vcc
	v_cmp_le_i32_e32 vcc, v2, v228
	v_or_b32_e32 v2, 57, v0
	s_nop 0
	v_cndmask_b32_e32 v92, v233, v92, vcc
	v_cmp_le_i32_e32 vcc, v2, v228
	v_or_b32_e32 v2, 58, v0
	v_or_b32_e32 v0, 59, v0
	v_cndmask_b32_e32 v93, v233, v93, vcc
	v_cmp_le_i32_e32 vcc, v2, v228
	s_nop 1
	v_cndmask_b32_e32 v94, v233, v94, vcc
	v_cmp_le_i32_e32 vcc, v0, v228
	s_nop 1
	v_cndmask_b32_e32 v95, v233, v95, vcc

; #define ATT_WV(n, x) asm volatile("s_waitcnt lgkmcnt(" #n ")" : "+v"(x) :: "memory")
; __device__ __forceinline__ void attn_phase(LAS unsigned char* ldsb, bf16_t* P, const bf16_t* Kn, const bf16_t* KPE, const bf16_t* VT) {
;     ...
;                     float ps = 0.f;
; #pragma unroll
;                     for (int kb = 0; kb < 2; ++kb)
; #pragma unroll
;                         for (int i = 0; i < 16; ++i) { const float p = __builtin_amdgcn_exp2f(st[kb][i] - mrun); st[kb][i] = p; ps += p; }
;                     lrun += ps;
;                     bf16x8 pb[2][2];
; #pragma unroll
;                     for (int kb = 0; kb < 2; ++kb)
; #pragma unroll
;                         for (int s2 = 0; s2 < 2; ++s2) {
;                             u32x4 pw; pw.x = pk2(st[kb][8 * s2 + 0], st[kb][8 * s2 + 1]); pw.y = pk2(st[kb][8 * s2 + 2], st[kb][8 * s2 + 3]);
;                             pw.z = pk2(st[kb][8 * s2 + 4], st[kb][8 * s2 + 5]); pw.w = pk2(st[kb][8 * s2 + 6], st[kb][8 * s2 + 7]);
;                             pb[kb][s2] = __builtin_bit_cast(bf16x8, pw); }
;                     {
;                         const unsigned va0 = (unsigned)(size_t)(sVt + r * 68 + 4 * hh), va1 = va0 + 32 * 68 * 2, va2 = va0 + 64 * 68 * 2, va3 = va0 + 96 * 68 * 2;
;                         bf16x8 vfa, vfb;
;     ...
;                         ATT_RV(vfa, va0, 0, 2);
;                         ATT_RV(vfb, va1, 0, 2); ATT_WV(1, vfa); o[0] = __builtin_amdgcn_mfma_f32_32x32x16_bf16(vfa, pb[0][0], o[0], 0, 0, 0);
;                         ATT_RV(vfa, va2, 0, 2); ATT_WV(1, vfb); o[1] = __builtin_amdgcn_mfma_f32_32x32x16_bf16(vfb, pb[0][0], o[1], 0, 0, 0);
;                         ATT_RV(vfb, va3, 0, 2); ATT_WV(1, vfa); o[2] = __builtin_amdgcn_mfma_f32_32x32x16_bf16(vfa, pb[0][0], o[2], 0, 0, 0);
;                         ATT_RV(vfa, va0, 4, 6); ATT_WV(1, vfb); o[3] = __builtin_amdgcn_mfma_f32_32x32x16_bf16(vfb, pb[0][0], o[3], 0, 0, 0);
;                         ATT_RV(vfb, va1, 4, 6); ATT_WV(1, vfa); o[0] = __builtin_amdgcn_mfma_f32_32x32x16_bf16(vfa, pb[0][1], o[0], 0, 0, 0);
;                         ATT_RV(vfa, va2, 4, 6); ATT_WV(1, vfb); o[1] = __builtin_amdgcn_mfma_f32_32x32x16_bf16(vfb, pb[0][1], o[1], 0, 0, 0);
;                         ATT_RV(vfb, va3, 4, 6); ATT_WV(1, vfa); o[2] = __builtin_amdgcn_mfma_f32_32x32x16_bf16(vfa, pb[0][1], o[2], 0, 0, 0);
.LBB0_1538:
	v_sub_f32_e32 v5, v96, v240
	v_exp_f32_e32 v5, v5
	v_sub_f32_e32 v6, v97, v240
	v_exp_f32_e32 v6, v6
	v_sub_f32_e32 v7, v98, v240
	v_exp_f32_e32 v7, v7
	v_sub_f32_e32 v8, v99, v240
	v_exp_f32_e32 v8, v8
	v_sub_f32_e32 v10, v100, v240
	v_add_f32_e32 v9, 0, v5
	v_exp_f32_e32 v10, v10
	v_sub_f32_e32 v11, v101, v240
	v_add_f32_e32 v9, v6, v9
	v_exp_f32_e32 v11, v11
	v_sub_f32_e32 v12, v102, v240
	v_add_f32_e32 v9, v7, v9
	v_exp_f32_e32 v12, v12
	v_sub_f32_e32 v13, v103, v240
	v_add_f32_e32 v9, v8, v9
	v_exp_f32_e32 v13, v13
	v_sub_f32_e32 v14, v104, v240
	v_add_f32_e32 v9, v10, v9
	v_exp_f32_e32 v14, v14
	v_sub_f32_e32 v15, v105, v240
	v_add_f32_e32 v9, v11, v9
	v_exp_f32_e32 v15, v15
	v_sub_f32_e32 v96, v106, v240
	v_add_f32_e32 v9, v12, v9
	v_exp_f32_e32 v96, v96
	v_sub_f32_e32 v97, v107, v240
	v_add_f32_e32 v9, v13, v9
	v_exp_f32_e32 v97, v97
	v_sub_f32_e32 v98, v108, v240
	v_add_f32_e32 v9, v14, v9
	v_exp_f32_e32 v98, v98
	v_sub_f32_e32 v99, v109, v240
	v_add_f32_e32 v9, v15, v9
	v_exp_f32_e32 v99, v99
	v_sub_f32_e32 v100, v110, v240
	v_add_f32_e32 v9, v96, v9
	v_exp_f32_e32 v100, v100
	v_sub_f32_e32 v101, v111, v240
	v_add_f32_e32 v9, v97, v9
	v_exp_f32_e32 v101, v101
	v_add_f32_e32 v9, v98, v9
	v_add_f32_e32 v9, v99, v9
	v_add_f32_e32 v9, v100, v9
	v_add_f32_e32 v102, v101, v9
	v_sub_f32_e32 v9, v80, v240
	v_exp_f32_e32 v103, v9
	v_sub_f32_e32 v9, v81, v240
	v_exp_f32_e32 v104, v9
	v_sub_f32_e32 v9, v82, v240
	v_exp_f32_e32 v105, v9
	v_sub_f32_e32 v9, v83, v240
	v_exp_f32_e32 v106, v9
	v_sub_f32_e32 v9, v84, v240
	v_exp_f32_e32 v107, v9
	v_sub_f32_e32 v9, v85, v240
	v_exp_f32_e32 v108, v9
	v_sub_f32_e32 v9, v86, v240
	v_exp_f32_e32 v109, v9
	v_sub_f32_e32 v9, v87, v240
	v_exp_f32_e32 v110, v9
	v_sub_f32_e32 v9, v88, v240
	v_exp_f32_e32 v111, v9
	v_sub_f32_e32 v9, v89, v240
	v_exp_f32_e32 v176, v9
	v_sub_f32_e32 v9, v90, v240
	v_exp_f32_e32 v177, v9
	v_sub_f32_e32 v9, v91, v240
	v_exp_f32_e32 v178, v9
	v_sub_f32_e32 v9, v92, v240
	v_exp_f32_e32 v92, v9
	v_sub_f32_e32 v9, v93, v240
	v_exp_f32_e32 v93, v9
	v_sub_f32_e32 v9, v94, v240
	v_exp_f32_e32 v94, v9
	v_cvt_pk_bf16_f32 v7, v7, v8
	v_cvt_pk_bf16_f32 v8, v10, v11
	v_cvt_pk_bf16_f32 v9, v12, v13
	ds_read_b128 v[10:13], v239 offset:0
	ds_read_b128 v[80:83], v238 offset:0
	v_cvt_pk_bf16_f32 v6, v5, v6
	s_waitcnt lgkmcnt(1)
	v_sub_f32_e32 v5, v95, v240
	v_exp_f32_e32 v5, v5
	v_mfma_f32_32x32x16_bf16 v[160:175], v[10:13], v[6:9], v[160:175]
	ds_read_b128 v[10:13], v237 offset:0
	s_waitcnt lgkmcnt(1)
	ds_read_b128 v[84:87], v235 offset:0
	s_mov_b64 s[6:7], 0
	s_waitcnt lgkmcnt(1)
	v_mfma_f32_32x32x16_bf16 v[144:159], v[80:83], v[6:9], v[144:159]
	v_cvt_pk_bf16_f32 v80, v14, v15
	v_cvt_pk_bf16_f32 v81, v96, v97
	v_cvt_pk_bf16_f32 v82, v98, v99
	v_cvt_pk_bf16_f32 v83, v100, v101
	v_add_f32_e32 v14, v103, v102
	v_add_f32_e32 v14, v104, v14
	v_mfma_f32_32x32x16_bf16 v[128:143], v[10:13], v[6:9], v[128:143]
	ds_read_b128 v[10:13], v239 offset:32
	s_waitcnt lgkmcnt(1)
	s_nop 0
	v_mfma_f32_32x32x16_bf16 v[112:127], v[84:87], v[6:9], v[112:127]
	ds_read_b128 v[84:87], v238 offset:32
	s_waitcnt lgkmcnt(1)
	v_cvt_pk_bf16_f32 v6, v103, v104
	v_cvt_pk_bf16_f32 v7, v105, v106
	v_cvt_pk_bf16_f32 v8, v107, v108
	v_cvt_pk_bf16_f32 v9, v109, v110
	v_mfma_f32_32x32x16_bf16 v[160:175], v[10:13], v[80:83], v[160:175]
	ds_read_b128 v[10:13], v237 offset:32
	s_waitcnt lgkmcnt(1)
	ds_read_b128 v[88:91], v235 offset:32
	s_nop 0
	s_waitcnt lgkmcnt(1)
	v_mfma_f32_32x32x16_bf16 v[144:159], v[84:87], v[80:83], v[144:159]
	v_cvt_pk_bf16_f32 v84, v111, v176
	v_cvt_pk_bf16_f32 v85, v177, v178
	v_cvt_pk_bf16_f32 v86, v92, v93
	v_cvt_pk_bf16_f32 v87, v94, v5
	v_mfma_f32_32x32x16_bf16 v[128:143], v[10:13], v[80:83], v[128:143]
	ds_read_b128 v[10:13], v239 offset:64
	s_waitcnt lgkmcnt(1)
	s_nop 0
	v_mfma_f32_32x32x16_bf16 v[112:127], v[88:91], v[80:83], v[112:127]
	ds_read_b128 v[80:83], v238 offset:64
	s_waitcnt lgkmcnt(1)
	s_nop 0
	v_mfma_f32_32x32x16_bf16 v[160:175], v[10:13], v[6:9], v[160:175]
	v_add_f32_e32 v10, v105, v14
	v_add_f32_e32 v14, v106, v10
	ds_read_b128 v[10:13], v237 offset:64
	s_waitcnt lgkmcnt(1)
	v_add_f32_e32 v14, v107, v14
	v_add_f32_e32 v14, v108, v14
	v_mfma_f32_32x32x16_bf16 v[144:159], v[80:83], v[6:9], v[144:159]
	ds_read_b128 v[80:83], v235 offset:64
	s_waitcnt lgkmcnt(1)
	s_nop 0
	v_mfma_f32_32x32x16_bf16 v[128:143], v[10:13], v[6:9], v[128:143]
	v_add_f32_e32 v10, v109, v14
	v_add_f32_e32 v14, v110, v10
	ds_read_b128 v[10:13], v239 offset:96
	s_waitcnt lgkmcnt(1)
	s_nop 0
	v_mfma_f32_32x32x16_bf16 v[112:127], v[80:83], v[6:9], v[112:127]
	v_add_f32_e32 v6, v111, v14
	v_add_f32_e32 v14, v176, v6
	ds_read_b128 v[6:9], v238 offset:96
	s_waitcnt lgkmcnt(1)
	s_nop 0
	v_mfma_f32_32x32x16_bf16 v[160:175], v[10:13], v[84:87], v[160:175]
	v_add_f32_e32 v10, v177, v14
	v_add_f32_e32 v14, v178, v10
	ds_read_b128 v[10:13], v237 offset:96
	s_waitcnt lgkmcnt(1)
	s_nop 0
	v_mfma_f32_32x32x16_bf16 v[144:159], v[6:9], v[84:87], v[144:159]
	v_add_f32_e32 v6, v92, v14
	v_add_f32_e32 v14, v93, v6
	ds_read_b128 v[6:9], v235 offset:96
	s_waitcnt lgkmcnt(1)
	s_nop 0
	s_waitcnt lgkmcnt(0)
	v_mfma_f32_32x32x16_bf16 v[128:143], v[10:13], v[84:87], v[128:143]
	v_add_f32_e32 v10, v94, v14
	v_add_f32_e32 v5, v5, v10
	v_add_f32_e32 v4, v4, v5
	v_mfma_f32_32x32x16_bf16 v[112:127], v[6:9], v[84:87], v[112:127]
